# proj GEMM loop: LDS-DMA 3-stage ring of BK=32 slices (swizzled 64B rows) instead of load-wait-ds_write single stage
# speedup vs baseline: 1.0848x; 1.0085x over previous
.LBB0_480:
	s_mul_hi_u32 s5, s4, 0xcccccccd
	s_lshr_b32 s6, s5, 9
	s_mulk_i32 s6, 0x280
	s_sub_i32 s4, s4, s6
	s_lshr_b32 s6, s5, 5
	s_mul_i32 s7, s4, 0xcccd
	s_and_b32 s6, s6, 0x3ffffc0
	s_lshr_b32 s7, s7, 19
	s_add_i32 s6, s6, s7
	s_mul_i32 s7, s7, 10
	s_bfe_u32 s5, s5, 0x20009
	s_sub_i32 s4, s4, s7
	s_mul_i32 s5, s5, 10
	s_and_b32 s4, s4, 0xffff
	s_mul_i32 s6, s6, 40
	s_add_i32 s4, s5, s4
	s_add_i32 s4, s4, s6
	s_mul_hi_u32 s5, s4, 0xcccccccd
	s_lshr_b32 s5, s5, 5
	s_lshl_b32 s96, s5, 8
	s_mul_i32 s5, s5, 40
	s_sub_i32 s7, s4, s5
	s_lshl_b64 s[4:5], s[96:97], 11
	s_add_u32 s38, s0, s4
	v_mov_b32_e32 v0, v133
	s_addc_u32 s39, s1, s5
	s_lshl_b32 s4, s7, 18
	s_add_u32 s40, s14, s4
	v_lshlrev_b32_e32 v2, 3, v0
	v_and_b32_e32 v2, 56, v2
	v_lshlrev_b32_e32 v3, 7, v0
	s_movk_i32 s4, 0xfc00
	v_lshrrev_b32_e32 v4, 1, v0
	v_and_or_b32 v131, v3, s4, v2
	v_lshlrev_b32_e32 v3, 1, v2
	v_and_b32_e32 v2, 0x5f, v0
	v_and_b32_e32 v4, 16, v4
	v_mad_u32_u24 v175, v2, s37, v4
	v_and_b32_e32 v2, 0xfffff9f, v0
	v_mul_lo_u32 v5, v2, s37
	v_lshrrev_b32_e32 v2, 3, v0
	v_mul_lo_u32 v6, v2, s37
	v_add_u32_e32 v2, 0x100, v0
	v_lshrrev_b32_e32 v2, 3, v2
	v_mul_lo_u32 v7, v2, s37
	v_add_u32_e32 v2, 0x200, v0
	v_lshrrev_b32_e32 v2, 3, v2
	v_mul_lo_u32 v8, v2, s37
	v_add_u32_e32 v2, 0x300, v0
	v_lshrrev_b32_e32 v2, 3, v2
	v_mul_lo_u32 v9, v2, s37
	v_add_u32_e32 v2, 0x400, v0
	v_lshrrev_b32_e32 v2, 3, v2
	v_mul_lo_u32 v10, v2, s37
	v_add_u32_e32 v2, 0x500, v0
	v_lshrrev_b32_e32 v2, 3, v2
	v_mul_lo_u32 v11, v2, s37
	v_add_u32_e32 v2, 0x600, v0
	v_lshrrev_b32_e32 v2, 3, v2
	v_mul_lo_u32 v12, v2, s37
	v_add_u32_e32 v2, 0x700, v0
	v_lshrrev_b32_e32 v2, 3, v2
	v_or_b32_e32 v0, 0x60, v0
	v_add_u32_e32 v135, 0x8000, v131
	v_add_u32_e32 v137, 0x10000, v131
	v_add_u32_e32 v152, 0x18000, v131
	v_add_u32_e32 v156, 0x20000, v131
	v_add_u32_e32 v172, 0x28000, v131
	v_add_u32_e32 v173, 0x30000, v131
	v_add_u32_e32 v174, 0x38000, v131
	v_mul_lo_u32 v13, v2, s37
	v_mul_lo_u32 v0, v0, s37
	v_mov_b32_e32 v2, 0
	s_addc_u32 s41, s15, 0
	s_mov_b32 s4, 1
	v_add_u32_e32 v176, v3, v6
	v_add_u32_e32 v177, v3, v7
	v_add_u32_e32 v178, v3, v8
	v_add_u32_e32 v179, v3, v9
	v_add_u32_e32 v180, v3, v10
	v_add_u32_e32 v181, v3, v11
	v_add_u32_e32 v182, v3, v12
	v_add_u32_e32 v183, v3, v13
	v_add_u32_e32 v213, v4, v5
	v_add_u32_e32 v214, v4, v0
	v_mov_b32_e32 v158, v174
	v_mov_b32_e32 v160, v173
	v_mov_b32_e32 v162, v172
	v_mov_b32_e32 v164, v156
	v_mov_b32_e32 v166, v152
	v_mov_b32_e32 v168, v137
	v_mov_b32_e32 v170, v135
	v_mov_b32_e32 v0, v131
	v_mov_b32_e32 v3, v2
	v_mov_b32_e32 v4, v2
	v_mov_b32_e32 v5, v2
	v_mov_b32_e32 v6, v2
	v_mov_b32_e32 v7, v2
	v_mov_b32_e32 v8, v2
	v_mov_b32_e32 v9, v2
	v_mov_b32_e32 v10, v2
	v_mov_b32_e32 v11, v2
	v_mov_b32_e32 v12, v2
	v_mov_b32_e32 v13, v2
	v_mov_b32_e32 v14, v2
	v_mov_b32_e32 v15, v2
	v_mov_b32_e32 v16, v2
	v_mov_b32_e32 v17, v2
	v_mov_b32_e32 v18, v2
	v_mov_b32_e32 v19, v2
	v_mov_b32_e32 v20, v2
	v_mov_b32_e32 v21, v2
	v_mov_b32_e32 v22, v2
	v_mov_b32_e32 v23, v2
	v_mov_b32_e32 v24, v2
	v_mov_b32_e32 v25, v2
	v_mov_b32_e32 v26, v2
	v_mov_b32_e32 v27, v2
	v_mov_b32_e32 v28, v2
	v_mov_b32_e32 v29, v2
	v_mov_b32_e32 v30, v2
	v_mov_b32_e32 v31, v2
	v_mov_b32_e32 v32, v2
	v_mov_b32_e32 v33, v2
	v_mov_b32_e32 v34, v2
	v_mov_b32_e32 v35, v2
	v_mov_b32_e32 v36, v2
	v_mov_b32_e32 v37, v2
	v_mov_b32_e32 v38, v2
	v_mov_b32_e32 v39, v2
	v_mov_b32_e32 v40, v2
	v_mov_b32_e32 v41, v2
	v_mov_b32_e32 v42, v2
	v_mov_b32_e32 v43, v2
	v_mov_b32_e32 v44, v2
	v_mov_b32_e32 v45, v2
	v_mov_b32_e32 v46, v2
	v_mov_b32_e32 v47, v2
	v_mov_b32_e32 v48, v2
	v_mov_b32_e32 v49, v2
	s_waitcnt vmcnt(3)
	v_mov_b32_e32 v50, v2
	s_waitcnt vmcnt(2)
	v_mov_b32_e32 v51, v2
	v_mov_b32_e32 v52, v2
	s_waitcnt vmcnt(1)
	v_mov_b32_e32 v53, v2
	v_mov_b32_e32 v54, v2
	v_mov_b32_e32 v55, v2
	v_mov_b32_e32 v56, v2
	v_mov_b32_e32 v57, v2
	v_mov_b32_e32 v58, v2
	v_mov_b32_e32 v59, v2
	v_mov_b32_e32 v60, v2
	v_mov_b32_e32 v61, v2
	v_mov_b32_e32 v62, v2
	v_mov_b32_e32 v63, v2
	v_mov_b32_e32 v64, v2
	v_mov_b32_e32 v65, v2
	v_mov_b32_e32 v66, v2
	v_mov_b32_e32 v67, v2
	v_mov_b32_e32 v68, v2
	v_mov_b32_e32 v69, v2
	v_mov_b32_e32 v70, v2
	v_mov_b32_e32 v71, v2
	v_mov_b32_e32 v72, v2
	v_mov_b32_e32 v73, v2
	v_mov_b32_e32 v74, v2
	v_mov_b32_e32 v75, v2
	v_mov_b32_e32 v76, v2
	v_mov_b32_e32 v77, v2
	v_mov_b32_e32 v78, v2
	v_mov_b32_e32 v79, v2
	v_mov_b32_e32 v80, v2
	v_mov_b32_e32 v81, v2
	v_mov_b32_e32 v82, v2
	v_mov_b32_e32 v83, v2
	v_mov_b32_e32 v84, v2
	v_mov_b32_e32 v85, v2
	v_mov_b32_e32 v86, v2
	v_mov_b32_e32 v87, v2
	v_mov_b32_e32 v88, v2
	v_mov_b32_e32 v89, v2
	v_mov_b32_e32 v90, v2
	v_mov_b32_e32 v91, v2
	v_mov_b32_e32 v92, v2
	v_mov_b32_e32 v93, v2
	v_mov_b32_e32 v94, v2
	v_mov_b32_e32 v95, v2
	v_mov_b32_e32 v96, v2
	v_mov_b32_e32 v97, v2
	v_mov_b32_e32 v98, v2
	v_mov_b32_e32 v99, v2
	v_mov_b32_e32 v100, v2
	v_mov_b32_e32 v101, v2
	v_mov_b32_e32 v102, v2
	v_mov_b32_e32 v103, v2
	v_mov_b32_e32 v104, v2
	v_mov_b32_e32 v105, v2
	v_mov_b32_e32 v106, v2
	v_mov_b32_e32 v107, v2
	v_mov_b32_e32 v108, v2
	v_mov_b32_e32 v109, v2
	v_mov_b32_e32 v110, v2
	v_mov_b32_e32 v111, v2
	v_mov_b32_e32 v112, v2
	v_mov_b32_e32 v113, v2
	v_mov_b32_e32 v114, v2
	v_mov_b32_e32 v115, v2
	v_mov_b32_e32 v116, v2
	v_mov_b32_e32 v117, v2
	v_mov_b32_e32 v118, v2
	v_mov_b32_e32 v119, v2
	v_mov_b32_e32 v120, v2
	v_mov_b32_e32 v121, v2
	v_mov_b32_e32 v122, v2
	v_mov_b32_e32 v123, v2
	v_mov_b32_e32 v124, v2
	v_mov_b32_e32 v125, v2
	v_mov_b32_e32 v126, v2
	v_mov_b32_e32 v127, v2
	v_mov_b32_e32 v128, v2
	v_mov_b32_e32 v129, v2
	v_and_b32_e32 v0, 63, v133
	v_lshrrev_b32_e32 v170, 6, v133
	v_lshlrev_b32_e32 v171, 10, v170
	v_lshrrev_b32_e32 v169, 2, v0
	v_readfirstlane_b32 s5, v171
	v_lshl_add_u32 v171, v170, 4, v169
	v_lshlrev_b32_e32 v171, 11, v171
	v_and_b32_e32 v166, 3, v0
	v_bfe_u32 v167, v0, 4, 2
	v_xor_b32_e32 v166, v166, v167
	v_lshl_add_u32 v158, v166, 4, v171
	v_add_u32_e32 v159, 0x20000, v158
	v_add_u32_e32 v160, 0x40000, v158
	v_add_u32_e32 v161, 0x60000, v158
	v_and_b32_e32 v166, 31, v0
	v_lshrrev_b32_e32 v167, 5, v0
	v_bfe_u32 v168, v0, 2, 2
	v_xor_b32_e32 v167, v167, v168
	v_lshrrev_b32_e32 v168, 1, v170
	v_and_b32_e32 v169, 1, v170
	v_lshl_add_u32 v168, v168, 7, v166
	v_lshl_add_u32 v169, v169, 6, v166
	v_lshlrev_b32_e32 v168, 6, v168
	v_lshlrev_b32_e32 v169, 6, v169
	v_add_u32_e32 v169, 0x4000, v169
	v_xor_b32_e32 v170, 2, v167
	v_lshl_add_u32 v162, v167, 4, v168
	v_lshl_add_u32 v163, v170, 4, v168
	v_lshl_add_u32 v164, v167, 4, v169
	v_lshl_add_u32 v165, v170, 4, v169
	s_waitcnt lgkmcnt(0)
	s_barrier
	s_add_u32 m0, s5, 0x0
	s_nop 0
	global_load_lds_dwordx4 v158, s[38:39]
	s_add_u32 m0, s5, 0x1000
	s_nop 0
	global_load_lds_dwordx4 v159, s[38:39]
	s_add_u32 m0, s5, 0x2000
	s_nop 0
	global_load_lds_dwordx4 v160, s[38:39]
	s_add_u32 m0, s5, 0x3000
	s_nop 0
	global_load_lds_dwordx4 v161, s[38:39]
	s_add_u32 m0, s5, 0x4000
	s_nop 0
	global_load_lds_dwordx4 v158, s[40:41]
	s_add_u32 m0, s5, 0x5000
	s_nop 0
	global_load_lds_dwordx4 v159, s[40:41]
	v_add_u32_e32 v158, 64, v158
	v_add_u32_e32 v159, 64, v159
	v_add_u32_e32 v160, 64, v160
	v_add_u32_e32 v161, 64, v161
	s_add_u32 m0, s5, 0x6000
	s_nop 0
	global_load_lds_dwordx4 v158, s[38:39]
	s_add_u32 m0, s5, 0x7000
	s_nop 0
	global_load_lds_dwordx4 v159, s[38:39]
	s_add_u32 m0, s5, 0x8000
	s_nop 0
	global_load_lds_dwordx4 v160, s[38:39]
	s_add_u32 m0, s5, 0x9000
	s_nop 0
	global_load_lds_dwordx4 v161, s[38:39]
	s_add_u32 m0, s5, 0xa000
	s_nop 0
	global_load_lds_dwordx4 v158, s[40:41]
	s_add_u32 m0, s5, 0xb000
	s_nop 0
	global_load_lds_dwordx4 v159, s[40:41]
	v_add_u32_e32 v158, 64, v158
	v_add_u32_e32 v159, 64, v159
	v_add_u32_e32 v160, 64, v160
	v_add_u32_e32 v161, 64, v161
	s_mov_b32 s4, 0
	s_waitcnt vmcnt(6)
.Lpj_loop:
	s_barrier
	ds_read_b128 v[216:219], v164
	ds_read_b128 v[232:235], v162
	ds_read_b128 v[220:223], v164 offset:2048
	ds_read_b128 v[236:239], v162 offset:2048
	ds_read_b128 v[240:243], v162 offset:4096
	ds_read_b128 v[244:247], v162 offset:6144
	ds_read_b128 v[224:227], v165
	ds_read_b128 v[228:231], v165 offset:2048
	ds_read_b128 v[248:251], v163
	ds_read_b128 v[166:169], v163 offset:2048
	s_waitcnt lgkmcnt(8)
	v_mfma_f32_32x32x16_bf16 v[114:129], v[232:235], v[216:219], v[114:129]
	s_waitcnt lgkmcnt(7)
	v_mfma_f32_32x32x16_bf16 v[98:113], v[232:235], v[220:223], v[98:113]
	ds_read_b128 v[232:235], v163 offset:4096
	s_add_u32 m0, s5, 0xc000
	s_nop 0
	global_load_lds_dwordx4 v158, s[38:39]
	s_waitcnt lgkmcnt(7)
	v_mfma_f32_32x32x16_bf16 v[82:97], v[236:239], v[216:219], v[82:97]
	v_mfma_f32_32x32x16_bf16 v[66:81], v[236:239], v[220:223], v[66:81]
	ds_read_b128 v[236:239], v163 offset:6144
	s_add_u32 m0, s5, 0xd000
	s_nop 0
	global_load_lds_dwordx4 v159, s[38:39]
	s_waitcnt lgkmcnt(7)
	v_mfma_f32_32x32x16_bf16 v[50:65], v[240:243], v[216:219], v[50:65]
	v_mfma_f32_32x32x16_bf16 v[34:49], v[240:243], v[220:223], v[34:49]
	s_add_u32 m0, s5, 0xe000
	s_nop 0
	global_load_lds_dwordx4 v160, s[38:39]
	s_waitcnt lgkmcnt(6)
	v_mfma_f32_32x32x16_bf16 v[18:33], v[244:247], v[216:219], v[18:33]
	v_mfma_f32_32x32x16_bf16 v[2:17], v[244:247], v[220:223], v[2:17]
	s_add_u32 m0, s5, 0xf000
	s_nop 0
	global_load_lds_dwordx4 v161, s[38:39]
	s_waitcnt lgkmcnt(3)
	v_mfma_f32_32x32x16_bf16 v[114:129], v[248:251], v[224:227], v[114:129]
	v_mfma_f32_32x32x16_bf16 v[98:113], v[248:251], v[228:231], v[98:113]
	s_add_u32 m0, s5, 0x10000
	s_nop 0
	global_load_lds_dwordx4 v158, s[40:41]
	s_waitcnt lgkmcnt(2)
	v_mfma_f32_32x32x16_bf16 v[82:97], v[166:169], v[224:227], v[82:97]
	v_mfma_f32_32x32x16_bf16 v[66:81], v[166:169], v[228:231], v[66:81]
	s_add_u32 m0, s5, 0x11000
	s_nop 0
	global_load_lds_dwordx4 v159, s[40:41]
	s_waitcnt lgkmcnt(1)
	v_mfma_f32_32x32x16_bf16 v[50:65], v[232:235], v[224:227], v[50:65]
	v_mfma_f32_32x32x16_bf16 v[34:49], v[232:235], v[228:231], v[34:49]
	v_add_u32_e32 v158, 64, v158
	v_add_u32_e32 v159, 64, v159
	v_add_u32_e32 v160, 64, v160
	v_add_u32_e32 v161, 64, v161
	s_waitcnt lgkmcnt(0)
	v_mfma_f32_32x32x16_bf16 v[18:33], v[236:239], v[224:227], v[18:33]
	v_mfma_f32_32x32x16_bf16 v[2:17], v[236:239], v[228:231], v[2:17]
	s_waitcnt vmcnt(6)
	s_barrier
	ds_read_b128 v[216:219], v164 offset:24576
	ds_read_b128 v[232:235], v162 offset:24576
	ds_read_b128 v[220:223], v164 offset:26624
	ds_read_b128 v[236:239], v162 offset:26624
	ds_read_b128 v[240:243], v162 offset:28672
	ds_read_b128 v[244:247], v162 offset:30720
	ds_read_b128 v[224:227], v165 offset:24576
	ds_read_b128 v[228:231], v165 offset:26624
	ds_read_b128 v[248:251], v163 offset:24576
	ds_read_b128 v[166:169], v163 offset:26624
	s_waitcnt lgkmcnt(8)
	v_mfma_f32_32x32x16_bf16 v[114:129], v[232:235], v[216:219], v[114:129]
	s_waitcnt lgkmcnt(7)
	v_mfma_f32_32x32x16_bf16 v[98:113], v[232:235], v[220:223], v[98:113]
	ds_read_b128 v[232:235], v163 offset:28672
	s_add_u32 m0, s5, 0x0
	s_nop 0
	global_load_lds_dwordx4 v158, s[38:39]
	s_waitcnt lgkmcnt(7)
	v_mfma_f32_32x32x16_bf16 v[82:97], v[236:239], v[216:219], v[82:97]
	v_mfma_f32_32x32x16_bf16 v[66:81], v[236:239], v[220:223], v[66:81]
	ds_read_b128 v[236:239], v163 offset:30720
	s_add_u32 m0, s5, 0x1000
	s_nop 0
	global_load_lds_dwordx4 v159, s[38:39]
	s_waitcnt lgkmcnt(7)
	v_mfma_f32_32x32x16_bf16 v[50:65], v[240:243], v[216:219], v[50:65]
	v_mfma_f32_32x32x16_bf16 v[34:49], v[240:243], v[220:223], v[34:49]
	s_add_u32 m0, s5, 0x2000
	s_nop 0
	global_load_lds_dwordx4 v160, s[38:39]
	s_waitcnt lgkmcnt(6)
	v_mfma_f32_32x32x16_bf16 v[18:33], v[244:247], v[216:219], v[18:33]
	v_mfma_f32_32x32x16_bf16 v[2:17], v[244:247], v[220:223], v[2:17]
	s_add_u32 m0, s5, 0x3000
	s_nop 0
	global_load_lds_dwordx4 v161, s[38:39]
	s_waitcnt lgkmcnt(3)
	v_mfma_f32_32x32x16_bf16 v[114:129], v[248:251], v[224:227], v[114:129]
	v_mfma_f32_32x32x16_bf16 v[98:113], v[248:251], v[228:231], v[98:113]
	s_add_u32 m0, s5, 0x4000
	s_nop 0
	global_load_lds_dwordx4 v158, s[40:41]
	s_waitcnt lgkmcnt(2)
	v_mfma_f32_32x32x16_bf16 v[82:97], v[166:169], v[224:227], v[82:97]
	v_mfma_f32_32x32x16_bf16 v[66:81], v[166:169], v[228:231], v[66:81]
	s_add_u32 m0, s5, 0x5000
	s_nop 0
	global_load_lds_dwordx4 v159, s[40:41]
	s_waitcnt lgkmcnt(1)
	v_mfma_f32_32x32x16_bf16 v[50:65], v[232:235], v[224:227], v[50:65]
	v_mfma_f32_32x32x16_bf16 v[34:49], v[232:235], v[228:231], v[34:49]
	v_add_u32_e32 v158, 64, v158
	v_add_u32_e32 v159, 64, v159
	v_add_u32_e32 v160, 64, v160
	v_add_u32_e32 v161, 64, v161
	s_waitcnt lgkmcnt(0)
	v_mfma_f32_32x32x16_bf16 v[18:33], v[236:239], v[224:227], v[18:33]
	v_mfma_f32_32x32x16_bf16 v[2:17], v[236:239], v[228:231], v[2:17]
	s_waitcnt vmcnt(6)
	s_barrier
	ds_read_b128 v[216:219], v164 offset:49152
	ds_read_b128 v[232:235], v162 offset:49152
	ds_read_b128 v[220:223], v164 offset:51200
	ds_read_b128 v[236:239], v162 offset:51200
	ds_read_b128 v[240:243], v162 offset:53248
	ds_read_b128 v[244:247], v162 offset:55296
	ds_read_b128 v[224:227], v165 offset:49152
	ds_read_b128 v[228:231], v165 offset:51200
	ds_read_b128 v[248:251], v163 offset:49152
	ds_read_b128 v[166:169], v163 offset:51200
	s_waitcnt lgkmcnt(8)
	v_mfma_f32_32x32x16_bf16 v[114:129], v[232:235], v[216:219], v[114:129]
	s_waitcnt lgkmcnt(7)
	v_mfma_f32_32x32x16_bf16 v[98:113], v[232:235], v[220:223], v[98:113]
	ds_read_b128 v[232:235], v163 offset:53248
	s_add_u32 m0, s5, 0x6000
	s_nop 0
	global_load_lds_dwordx4 v158, s[38:39]
	s_waitcnt lgkmcnt(7)
	v_mfma_f32_32x32x16_bf16 v[82:97], v[236:239], v[216:219], v[82:97]
	v_mfma_f32_32x32x16_bf16 v[66:81], v[236:239], v[220:223], v[66:81]
	ds_read_b128 v[236:239], v163 offset:55296
	s_add_u32 m0, s5, 0x7000
	s_nop 0
	global_load_lds_dwordx4 v159, s[38:39]
	s_waitcnt lgkmcnt(7)
	v_mfma_f32_32x32x16_bf16 v[50:65], v[240:243], v[216:219], v[50:65]
	v_mfma_f32_32x32x16_bf16 v[34:49], v[240:243], v[220:223], v[34:49]
	s_add_u32 m0, s5, 0x8000
	s_nop 0
	global_load_lds_dwordx4 v160, s[38:39]
	s_waitcnt lgkmcnt(6)
	v_mfma_f32_32x32x16_bf16 v[18:33], v[244:247], v[216:219], v[18:33]
	v_mfma_f32_32x32x16_bf16 v[2:17], v[244:247], v[220:223], v[2:17]
	s_add_u32 m0, s5, 0x9000
	s_nop 0
	global_load_lds_dwordx4 v161, s[38:39]
	s_waitcnt lgkmcnt(3)
	v_mfma_f32_32x32x16_bf16 v[114:129], v[248:251], v[224:227], v[114:129]
	v_mfma_f32_32x32x16_bf16 v[98:113], v[248:251], v[228:231], v[98:113]
	s_add_u32 m0, s5, 0xa000
	s_nop 0
	global_load_lds_dwordx4 v158, s[40:41]
	s_waitcnt lgkmcnt(2)
	v_mfma_f32_32x32x16_bf16 v[82:97], v[166:169], v[224:227], v[82:97]
	v_mfma_f32_32x32x16_bf16 v[66:81], v[166:169], v[228:231], v[66:81]
	s_add_u32 m0, s5, 0xb000
	s_nop 0
	global_load_lds_dwordx4 v159, s[40:41]
	s_waitcnt lgkmcnt(1)
	v_mfma_f32_32x32x16_bf16 v[50:65], v[232:235], v[224:227], v[50:65]
	v_mfma_f32_32x32x16_bf16 v[34:49], v[232:235], v[228:231], v[34:49]
	v_add_u32_e32 v158, 64, v158
	v_add_u32_e32 v159, 64, v159
	v_add_u32_e32 v160, 64, v160
	v_add_u32_e32 v161, 64, v161
	s_waitcnt lgkmcnt(0)
	v_mfma_f32_32x32x16_bf16 v[18:33], v[236:239], v[224:227], v[18:33]
	v_mfma_f32_32x32x16_bf16 v[2:17], v[236:239], v[228:231], v[2:17]
	s_waitcnt vmcnt(6)
	s_add_i32 s4, s4, 1
	s_cmp_lg_u32 s4, 10
	s_cbranch_scc1 .Lpj_loop
	s_barrier
	ds_read_b128 v[216:219], v164
	ds_read_b128 v[232:235], v162
	ds_read_b128 v[220:223], v164 offset:2048
	ds_read_b128 v[236:239], v162 offset:2048
	ds_read_b128 v[240:243], v162 offset:4096
	ds_read_b128 v[244:247], v162 offset:6144
	ds_read_b128 v[224:227], v165
	ds_read_b128 v[228:231], v165 offset:2048
	ds_read_b128 v[248:251], v163
	ds_read_b128 v[166:169], v163 offset:2048
	s_waitcnt lgkmcnt(8)
	v_mfma_f32_32x32x16_bf16 v[114:129], v[232:235], v[216:219], v[114:129]
	s_waitcnt lgkmcnt(7)
	v_mfma_f32_32x32x16_bf16 v[98:113], v[232:235], v[220:223], v[98:113]
	ds_read_b128 v[232:235], v163 offset:4096
	s_waitcnt lgkmcnt(7)
	v_mfma_f32_32x32x16_bf16 v[82:97], v[236:239], v[216:219], v[82:97]
	v_mfma_f32_32x32x16_bf16 v[66:81], v[236:239], v[220:223], v[66:81]
	ds_read_b128 v[236:239], v163 offset:6144
	s_waitcnt lgkmcnt(7)
	v_mfma_f32_32x32x16_bf16 v[50:65], v[240:243], v[216:219], v[50:65]
	v_mfma_f32_32x32x16_bf16 v[34:49], v[240:243], v[220:223], v[34:49]
	s_waitcnt lgkmcnt(6)
	v_mfma_f32_32x32x16_bf16 v[18:33], v[244:247], v[216:219], v[18:33]
	v_mfma_f32_32x32x16_bf16 v[2:17], v[244:247], v[220:223], v[2:17]
	s_waitcnt lgkmcnt(3)
	v_mfma_f32_32x32x16_bf16 v[114:129], v[248:251], v[224:227], v[114:129]
	v_mfma_f32_32x32x16_bf16 v[98:113], v[248:251], v[228:231], v[98:113]
	s_waitcnt lgkmcnt(2)
	v_mfma_f32_32x32x16_bf16 v[82:97], v[166:169], v[224:227], v[82:97]
	v_mfma_f32_32x32x16_bf16 v[66:81], v[166:169], v[228:231], v[66:81]
	s_waitcnt lgkmcnt(1)
	v_mfma_f32_32x32x16_bf16 v[50:65], v[232:235], v[224:227], v[50:65]
	v_mfma_f32_32x32x16_bf16 v[34:49], v[232:235], v[228:231], v[34:49]
	s_waitcnt lgkmcnt(0)
	v_mfma_f32_32x32x16_bf16 v[18:33], v[236:239], v[224:227], v[18:33]
	v_mfma_f32_32x32x16_bf16 v[2:17], v[236:239], v[228:231], v[2:17]
	s_waitcnt vmcnt(0)
	s_barrier
	ds_read_b128 v[216:219], v164 offset:24576
	ds_read_b128 v[232:235], v162 offset:24576
	ds_read_b128 v[220:223], v164 offset:26624
	ds_read_b128 v[236:239], v162 offset:26624
	ds_read_b128 v[240:243], v162 offset:28672
	ds_read_b128 v[244:247], v162 offset:30720
	ds_read_b128 v[224:227], v165 offset:24576
	ds_read_b128 v[228:231], v165 offset:26624
	ds_read_b128 v[248:251], v163 offset:24576
	ds_read_b128 v[166:169], v163 offset:26624
	s_waitcnt lgkmcnt(8)
	v_mfma_f32_32x32x16_bf16 v[114:129], v[232:235], v[216:219], v[114:129]
	s_waitcnt lgkmcnt(7)
	v_mfma_f32_32x32x16_bf16 v[98:113], v[232:235], v[220:223], v[98:113]
	ds_read_b128 v[232:235], v163 offset:28672
	s_waitcnt lgkmcnt(7)
	v_mfma_f32_32x32x16_bf16 v[82:97], v[236:239], v[216:219], v[82:97]
	v_mfma_f32_32x32x16_bf16 v[66:81], v[236:239], v[220:223], v[66:81]
	ds_read_b128 v[236:239], v163 offset:30720
	s_waitcnt lgkmcnt(7)
	v_mfma_f32_32x32x16_bf16 v[50:65], v[240:243], v[216:219], v[50:65]
	v_mfma_f32_32x32x16_bf16 v[34:49], v[240:243], v[220:223], v[34:49]
	s_waitcnt lgkmcnt(6)
	v_mfma_f32_32x32x16_bf16 v[18:33], v[244:247], v[216:219], v[18:33]
	v_mfma_f32_32x32x16_bf16 v[2:17], v[244:247], v[220:223], v[2:17]
	s_waitcnt lgkmcnt(3)
	v_mfma_f32_32x32x16_bf16 v[114:129], v[248:251], v[224:227], v[114:129]
	v_mfma_f32_32x32x16_bf16 v[98:113], v[248:251], v[228:231], v[98:113]
	s_waitcnt lgkmcnt(2)
	v_mfma_f32_32x32x16_bf16 v[82:97], v[166:169], v[224:227], v[82:97]
	v_mfma_f32_32x32x16_bf16 v[66:81], v[166:169], v[228:231], v[66:81]
	s_waitcnt lgkmcnt(1)
	v_mfma_f32_32x32x16_bf16 v[50:65], v[232:235], v[224:227], v[50:65]
	v_mfma_f32_32x32x16_bf16 v[34:49], v[232:235], v[228:231], v[34:49]
	s_waitcnt lgkmcnt(0)
	v_mfma_f32_32x32x16_bf16 v[18:33], v[236:239], v[224:227], v[18:33]
	v_mfma_f32_32x32x16_bf16 v[2:17], v[236:239], v[228:231], v[2:17]
	s_nop 15
	s_lshl_b32 s6, s7, 7
	v_mov_b32_e32 v137, v133
	v_mov_b32_e32 v0, v133
	s_cmp_gt_u32 s7, 3
	v_bfe_u32 v135, v0, 6, 1
	v_and_b32_e32 v131, 31, v137
	s_mov_b64 s[4:5], -1
	s_cbranch_scc0 .LBB0_509
	s_cmp_gt_u32 s7, 9
	s_cbranch_scc0 .LBB0_499
	s_cmp_gt_u32 s7, 21
	s_cbranch_scc0 .LBB0_496
	s_cmp_gt_u32 s7, 25
	s_cbranch_scc0 .LBB0_493
	s_cmp_gt_u32 s7, 38
	s_cbranch_scc0 .LBB0_490
	v_mov_b32_e32 v0, v133
	v_mov_b32_e32 v156, v133
	v_and_b32_e32 v152, 31, v0
	s_movk_i32 s4, 0x1398
	v_and_or_b32 v152, v156, 64, v152
	v_or_b32_e32 v158, 0x1380, v152
	v_cmp_gt_u32_e32 vcc, s4, v158
	s_and_saveexec_b64 s[4:5], vcc
	s_cbranch_execz .LBB0_489
	v_and_b32_e32 v156, 0xffffff80, v156
	v_add_u32_e32 v156, s96, v156
	v_lshrrev_b32_e32 v0, 3, v0
	v_and_or_b32 v158, v0, 4, v156
	v_readlane_b32 s8, v253, 19
	v_lshlrev_b32_e32 v0, 2, v152
	v_readlane_b32 s9, v253, 20
	v_ashrrev_i32_e32 v159, 31, v158
	v_lshlrev_b64 v[162:163], 7, v[158:159]
	v_lshl_add_u64 v[160:161], s[8:9], 0, v[0:1]
	v_lshl_add_u64 v[162:163], v[160:161], 0, v[162:163]
	global_store_dword v[162:163], v114, off
	v_or_b32_e32 v162, 1, v158
	v_ashrrev_i32_e32 v163, 31, v162
	v_lshlrev_b64 v[162:163], 7, v[162:163]
	v_lshl_add_u64 v[162:163], v[160:161], 0, v[162:163]
	global_store_dword v[162:163], v115, off
	v_or_b32_e32 v162, 2, v158
	v_ashrrev_i32_e32 v163, 31, v162
	v_lshlrev_b64 v[162:163], 7, v[162:163]
	v_lshl_add_u64 v[162:163], v[160:161], 0, v[162:163]
	global_store_dword v[162:163], v116, off
	v_or_b32_e32 v162, 3, v158
	v_ashrrev_i32_e32 v163, 31, v162
	v_lshlrev_b64 v[162:163], 7, v[162:163]
	v_lshl_add_u64 v[162:163], v[160:161], 0, v[162:163]
	global_store_dword v[162:163], v117, off
	v_or_b32_e32 v162, 8, v158
	v_ashrrev_i32_e32 v163, 31, v162
	v_lshlrev_b64 v[162:163], 7, v[162:163]
	v_lshl_add_u64 v[162:163], v[160:161], 0, v[162:163]
	global_store_dword v[162:163], v118, off
	v_or_b32_e32 v162, 9, v158
	v_ashrrev_i32_e32 v163, 31, v162
	v_lshlrev_b64 v[162:163], 7, v[162:163]
	v_lshl_add_u64 v[162:163], v[160:161], 0, v[162:163]
	global_store_dword v[162:163], v119, off
	v_or_b32_e32 v162, 10, v158
	v_ashrrev_i32_e32 v163, 31, v162
	v_lshlrev_b64 v[162:163], 7, v[162:163]
	v_lshl_add_u64 v[162:163], v[160:161], 0, v[162:163]
	global_store_dword v[162:163], v120, off
	v_or_b32_e32 v162, 11, v158
	v_ashrrev_i32_e32 v163, 31, v162
	v_lshlrev_b64 v[162:163], 7, v[162:163]
	v_lshl_add_u64 v[162:163], v[160:161], 0, v[162:163]
	global_store_dword v[162:163], v121, off
	v_or_b32_e32 v162, 16, v158
	v_ashrrev_i32_e32 v163, 31, v162
	v_lshlrev_b64 v[162:163], 7, v[162:163]
	v_lshl_add_u64 v[162:163], v[160:161], 0, v[162:163]
	global_store_dword v[162:163], v122, off
	v_or_b32_e32 v162, 17, v158
	v_ashrrev_i32_e32 v163, 31, v162
	v_lshlrev_b64 v[162:163], 7, v[162:163]
	v_lshl_add_u64 v[162:163], v[160:161], 0, v[162:163]
	global_store_dword v[162:163], v123, off
	v_or_b32_e32 v162, 18, v158
	v_ashrrev_i32_e32 v163, 31, v162
	v_lshlrev_b64 v[162:163], 7, v[162:163]
	v_lshl_add_u64 v[162:163], v[160:161], 0, v[162:163]
	global_store_dword v[162:163], v124, off
	v_or_b32_e32 v162, 19, v158
	v_ashrrev_i32_e32 v163, 31, v162
	v_lshlrev_b64 v[162:163], 7, v[162:163]
	v_lshl_add_u64 v[162:163], v[160:161], 0, v[162:163]
	global_store_dword v[162:163], v125, off
	v_or_b32_e32 v162, 24, v158
	v_ashrrev_i32_e32 v163, 31, v162
	v_lshlrev_b64 v[162:163], 7, v[162:163]
	v_lshl_add_u64 v[162:163], v[160:161], 0, v[162:163]
	global_store_dword v[162:163], v126, off
	v_or_b32_e32 v162, 25, v158
	v_ashrrev_i32_e32 v163, 31, v162
	v_lshlrev_b64 v[162:163], 7, v[162:163]
	v_lshl_add_u64 v[162:163], v[160:161], 0, v[162:163]
	global_store_dword v[162:163], v127, off
	v_or_b32_e32 v162, 26, v158
	v_ashrrev_i32_e32 v163, 31, v162
	v_lshlrev_b64 v[162:163], 7, v[162:163]
	v_lshl_add_u64 v[162:163], v[160:161], 0, v[162:163]
	global_store_dword v[162:163], v128, off
	v_or_b32_e32 v162, 27, v158
	v_ashrrev_i32_e32 v163, 31, v162
	v_lshlrev_b64 v[162:163], 7, v[162:163]
	v_lshl_add_u64 v[162:163], v[160:161], 0, v[162:163]
	global_store_dword v[162:163], v129, off
	v_or_b32_e32 v162, 32, v158
	v_ashrrev_i32_e32 v163, 31, v162
	v_lshlrev_b64 v[162:163], 7, v[162:163]
	v_lshl_add_u64 v[162:163], v[160:161], 0, v[162:163]
	global_store_dword v[162:163], v82, off
	v_or_b32_e32 v162, 33, v158
	v_ashrrev_i32_e32 v163, 31, v162
	v_lshlrev_b64 v[162:163], 7, v[162:163]
	v_lshl_add_u64 v[162:163], v[160:161], 0, v[162:163]
	global_store_dword v[162:163], v83, off
	v_or_b32_e32 v162, 34, v158
	v_ashrrev_i32_e32 v163, 31, v162
	v_lshlrev_b64 v[162:163], 7, v[162:163]
	v_lshl_add_u64 v[162:163], v[160:161], 0, v[162:163]
	global_store_dword v[162:163], v84, off
	v_or_b32_e32 v162, 35, v158
	v_ashrrev_i32_e32 v163, 31, v162
	v_lshlrev_b64 v[162:163], 7, v[162:163]
	v_lshl_add_u64 v[162:163], v[160:161], 0, v[162:163]
	global_store_dword v[162:163], v85, off
	v_or_b32_e32 v162, 40, v158
	v_ashrrev_i32_e32 v163, 31, v162
	v_lshlrev_b64 v[162:163], 7, v[162:163]
	v_lshl_add_u64 v[162:163], v[160:161], 0, v[162:163]
	global_store_dword v[162:163], v86, off
	v_or_b32_e32 v162, 41, v158
	v_ashrrev_i32_e32 v163, 31, v162
	v_lshlrev_b64 v[162:163], 7, v[162:163]
	v_lshl_add_u64 v[162:163], v[160:161], 0, v[162:163]
	global_store_dword v[162:163], v87, off
	v_or_b32_e32 v162, 42, v158
	v_ashrrev_i32_e32 v163, 31, v162
	v_lshlrev_b64 v[162:163], 7, v[162:163]
	v_lshl_add_u64 v[162:163], v[160:161], 0, v[162:163]
	global_store_dword v[162:163], v88, off
	v_or_b32_e32 v162, 43, v158
	v_ashrrev_i32_e32 v163, 31, v162
	v_lshlrev_b64 v[162:163], 7, v[162:163]
	v_lshl_add_u64 v[162:163], v[160:161], 0, v[162:163]
	global_store_dword v[162:163], v89, off
	v_or_b32_e32 v162, 48, v158
	v_ashrrev_i32_e32 v163, 31, v162
	v_lshlrev_b64 v[162:163], 7, v[162:163]
	v_lshl_add_u64 v[162:163], v[160:161], 0, v[162:163]
	global_store_dword v[162:163], v90, off
	v_or_b32_e32 v162, 49, v158
	v_ashrrev_i32_e32 v163, 31, v162
	v_lshlrev_b64 v[162:163], 7, v[162:163]
	v_lshl_add_u64 v[162:163], v[160:161], 0, v[162:163]
	global_store_dword v[162:163], v91, off
	v_or_b32_e32 v162, 50, v158
	v_ashrrev_i32_e32 v163, 31, v162
	v_lshlrev_b64 v[162:163], 7, v[162:163]
	v_lshl_add_u64 v[162:163], v[160:161], 0, v[162:163]
	global_store_dword v[162:163], v92, off
	v_or_b32_e32 v162, 51, v158
	v_ashrrev_i32_e32 v163, 31, v162
	v_lshlrev_b64 v[162:163], 7, v[162:163]
	v_lshl_add_u64 v[162:163], v[160:161], 0, v[162:163]
	global_store_dword v[162:163], v93, off
	v_or_b32_e32 v162, 56, v158
	v_ashrrev_i32_e32 v163, 31, v162
	v_lshlrev_b64 v[162:163], 7, v[162:163]
	v_lshl_add_u64 v[162:163], v[160:161], 0, v[162:163]
	global_store_dword v[162:163], v94, off
	v_or_b32_e32 v162, 57, v158
	v_ashrrev_i32_e32 v163, 31, v162
	v_lshlrev_b64 v[162:163], 7, v[162:163]
	v_lshl_add_u64 v[162:163], v[160:161], 0, v[162:163]
	global_store_dword v[162:163], v95, off
	v_or_b32_e32 v162, 58, v158
	v_ashrrev_i32_e32 v163, 31, v162
	v_lshlrev_b64 v[162:163], 7, v[162:163]
	v_lshl_add_u64 v[162:163], v[160:161], 0, v[162:163]
	global_store_dword v[162:163], v96, off
	v_or_b32_e32 v162, 59, v158
	v_ashrrev_i32_e32 v163, 31, v162
	v_lshlrev_b64 v[162:163], 7, v[162:163]
	v_lshl_add_u64 v[162:163], v[160:161], 0, v[162:163]
	global_store_dword v[162:163], v97, off
	v_or_b32_e32 v162, 64, v158
	v_ashrrev_i32_e32 v163, 31, v162
	v_lshlrev_b64 v[162:163], 7, v[162:163]
	v_lshl_add_u64 v[162:163], v[160:161], 0, v[162:163]
	global_store_dword v[162:163], v50, off
	v_or_b32_e32 v162, 0x41, v158
	v_ashrrev_i32_e32 v163, 31, v162
	v_lshlrev_b64 v[162:163], 7, v[162:163]
	v_lshl_add_u64 v[162:163], v[160:161], 0, v[162:163]
	global_store_dword v[162:163], v51, off
	v_or_b32_e32 v162, 0x42, v158
	v_ashrrev_i32_e32 v163, 31, v162
	v_lshlrev_b64 v[162:163], 7, v[162:163]
	v_lshl_add_u64 v[162:163], v[160:161], 0, v[162:163]
	global_store_dword v[162:163], v52, off
	v_or_b32_e32 v162, 0x43, v158
	v_ashrrev_i32_e32 v163, 31, v162
	v_lshlrev_b64 v[162:163], 7, v[162:163]
	v_lshl_add_u64 v[162:163], v[160:161], 0, v[162:163]
	global_store_dword v[162:163], v53, off
	v_or_b32_e32 v162, 0x48, v158
	v_ashrrev_i32_e32 v163, 31, v162
	v_lshlrev_b64 v[162:163], 7, v[162:163]
	v_lshl_add_u64 v[162:163], v[160:161], 0, v[162:163]
	global_store_dword v[162:163], v54, off
	v_or_b32_e32 v162, 0x49, v158
	v_ashrrev_i32_e32 v163, 31, v162
	v_lshlrev_b64 v[162:163], 7, v[162:163]
	v_lshl_add_u64 v[162:163], v[160:161], 0, v[162:163]
	global_store_dword v[162:163], v55, off
	v_or_b32_e32 v162, 0x4a, v158
	v_ashrrev_i32_e32 v163, 31, v162
	v_lshlrev_b64 v[162:163], 7, v[162:163]
	v_lshl_add_u64 v[162:163], v[160:161], 0, v[162:163]
	global_store_dword v[162:163], v56, off
	v_or_b32_e32 v162, 0x4b, v158
	v_ashrrev_i32_e32 v163, 31, v162
	v_lshlrev_b64 v[162:163], 7, v[162:163]
	v_lshl_add_u64 v[162:163], v[160:161], 0, v[162:163]
	global_store_dword v[162:163], v57, off
	v_or_b32_e32 v162, 0x50, v158
	v_ashrrev_i32_e32 v163, 31, v162
	v_lshlrev_b64 v[162:163], 7, v[162:163]
	v_lshl_add_u64 v[162:163], v[160:161], 0, v[162:163]
	global_store_dword v[162:163], v58, off
	v_or_b32_e32 v162, 0x51, v158
	v_ashrrev_i32_e32 v163, 31, v162
	v_lshlrev_b64 v[162:163], 7, v[162:163]
	v_lshl_add_u64 v[162:163], v[160:161], 0, v[162:163]
	global_store_dword v[162:163], v59, off
	v_or_b32_e32 v162, 0x52, v158
	v_ashrrev_i32_e32 v163, 31, v162
	v_lshlrev_b64 v[162:163], 7, v[162:163]
	v_lshl_add_u64 v[162:163], v[160:161], 0, v[162:163]
	global_store_dword v[162:163], v60, off
	v_or_b32_e32 v162, 0x53, v158
	v_ashrrev_i32_e32 v163, 31, v162
	v_lshlrev_b64 v[162:163], 7, v[162:163]
	v_lshl_add_u64 v[162:163], v[160:161], 0, v[162:163]
	global_store_dword v[162:163], v61, off
	v_or_b32_e32 v162, 0x58, v158
	v_ashrrev_i32_e32 v163, 31, v162
	v_lshlrev_b64 v[162:163], 7, v[162:163]
	v_lshl_add_u64 v[162:163], v[160:161], 0, v[162:163]
	global_store_dword v[162:163], v62, off
	v_or_b32_e32 v162, 0x59, v158
	v_ashrrev_i32_e32 v163, 31, v162
	v_lshlrev_b64 v[162:163], 7, v[162:163]
	v_lshl_add_u64 v[162:163], v[160:161], 0, v[162:163]
	global_store_dword v[162:163], v63, off
	v_or_b32_e32 v162, 0x5a, v158
	v_ashrrev_i32_e32 v163, 31, v162
	v_lshlrev_b64 v[162:163], 7, v[162:163]
	v_lshl_add_u64 v[162:163], v[160:161], 0, v[162:163]
	global_store_dword v[162:163], v64, off
	v_or_b32_e32 v162, 0x5b, v158
	v_ashrrev_i32_e32 v163, 31, v162
	v_lshlrev_b64 v[162:163], 7, v[162:163]
	v_lshl_add_u64 v[162:163], v[160:161], 0, v[162:163]
	global_store_dword v[162:163], v65, off
	v_or_b32_e32 v162, 0x60, v158
	v_ashrrev_i32_e32 v163, 31, v162
	v_lshlrev_b64 v[162:163], 7, v[162:163]
	v_lshl_add_u64 v[162:163], v[160:161], 0, v[162:163]
	global_store_dword v[162:163], v18, off
	v_or_b32_e32 v162, 0x61, v158
	v_ashrrev_i32_e32 v163, 31, v162
	v_lshlrev_b64 v[162:163], 7, v[162:163]
	v_lshl_add_u64 v[162:163], v[160:161], 0, v[162:163]
	global_store_dword v[162:163], v19, off
	v_or_b32_e32 v162, 0x62, v158
	v_ashrrev_i32_e32 v163, 31, v162
	v_lshlrev_b64 v[162:163], 7, v[162:163]
	v_lshl_add_u64 v[162:163], v[160:161], 0, v[162:163]
	global_store_dword v[162:163], v20, off
	v_or_b32_e32 v162, 0x63, v158
	v_ashrrev_i32_e32 v163, 31, v162
	v_lshlrev_b64 v[162:163], 7, v[162:163]
	v_lshl_add_u64 v[162:163], v[160:161], 0, v[162:163]
	global_store_dword v[162:163], v21, off
	v_or_b32_e32 v162, 0x68, v158
	v_ashrrev_i32_e32 v163, 31, v162
	v_lshlrev_b64 v[162:163], 7, v[162:163]
	v_lshl_add_u64 v[162:163], v[160:161], 0, v[162:163]
	global_store_dword v[162:163], v22, off
	v_or_b32_e32 v162, 0x69, v158
	v_ashrrev_i32_e32 v163, 31, v162
	v_lshlrev_b64 v[162:163], 7, v[162:163]
	v_lshl_add_u64 v[162:163], v[160:161], 0, v[162:163]
	global_store_dword v[162:163], v23, off
	v_or_b32_e32 v162, 0x6a, v158
	v_ashrrev_i32_e32 v163, 31, v162
	v_lshlrev_b64 v[162:163], 7, v[162:163]
	v_lshl_add_u64 v[162:163], v[160:161], 0, v[162:163]
	global_store_dword v[162:163], v24, off
	v_or_b32_e32 v162, 0x6b, v158
	v_ashrrev_i32_e32 v163, 31, v162
	v_lshlrev_b64 v[162:163], 7, v[162:163]
	v_lshl_add_u64 v[162:163], v[160:161], 0, v[162:163]
	global_store_dword v[162:163], v25, off
	v_or_b32_e32 v162, 0x70, v158
	v_ashrrev_i32_e32 v163, 31, v162
	v_lshlrev_b64 v[162:163], 7, v[162:163]
	v_lshl_add_u64 v[162:163], v[160:161], 0, v[162:163]
	global_store_dword v[162:163], v26, off
	v_or_b32_e32 v162, 0x71, v158
	v_ashrrev_i32_e32 v163, 31, v162
	v_lshlrev_b64 v[162:163], 7, v[162:163]
	v_lshl_add_u64 v[162:163], v[160:161], 0, v[162:163]
	global_store_dword v[162:163], v27, off
	v_or_b32_e32 v162, 0x72, v158
	v_ashrrev_i32_e32 v163, 31, v162
	v_lshlrev_b64 v[162:163], 7, v[162:163]
	v_lshl_add_u64 v[162:163], v[160:161], 0, v[162:163]
	global_store_dword v[162:163], v28, off
	v_or_b32_e32 v162, 0x73, v158
	v_ashrrev_i32_e32 v163, 31, v162
	v_lshlrev_b64 v[162:163], 7, v[162:163]
	v_lshl_add_u64 v[162:163], v[160:161], 0, v[162:163]
	global_store_dword v[162:163], v29, off
	v_or_b32_e32 v162, 0x78, v158
	v_ashrrev_i32_e32 v163, 31, v162
	v_lshlrev_b64 v[162:163], 7, v[162:163]
	v_lshl_add_u64 v[162:163], v[160:161], 0, v[162:163]
	global_store_dword v[162:163], v30, off
	v_or_b32_e32 v162, 0x79, v158
	v_ashrrev_i32_e32 v163, 31, v162
	v_lshlrev_b64 v[162:163], 7, v[162:163]
	v_lshl_add_u64 v[162:163], v[160:161], 0, v[162:163]
	global_store_dword v[162:163], v31, off
	v_or_b32_e32 v162, 0x7a, v158
	v_or_b32_e32 v158, 0x7b, v158
	v_ashrrev_i32_e32 v163, 31, v162
	v_ashrrev_i32_e32 v159, 31, v158
	v_lshlrev_b64 v[162:163], 7, v[162:163]
	v_lshlrev_b64 v[158:159], 7, v[158:159]
	v_lshl_add_u64 v[162:163], v[160:161], 0, v[162:163]
	v_lshl_add_u64 v[158:159], v[160:161], 0, v[158:159]
	global_store_dword v[162:163], v32, off
	global_store_dword v[158:159], v33, off
